# v38 + silu(c) table loop at kernel start unrolled: 16 independent loads instead of 16 serialized load-wait steps
# speedup vs baseline: 1.0062x; 1.0062x over previous
; __device__ __forceinline__ float siluf_(float x) { return x * sigmoidf_(x); }
; __global__ void __launch_bounds__(NWAVES * 64, 2) fwd_kernel(Args args) {
;     ...
;             for (int i = tid; i < BATCH * D; i += NWAVES * 64) { const float v = cvec[i]; cact[i] = pg8::siluf_(v); }
;             __syncthreads();
;             const int cg = tid % 24, kg = tid / 24;
.LBB0_15:
	s_mov_b64 s[2:3], 0x1000
	global_load_dword v10, v[2:3], off
	global_load_dword v11, v[2:3], off offset:2048
	v_lshl_add_u64 v[2:3], v[2:3], 0, s[2:3]
	global_load_dword v12, v[2:3], off
	global_load_dword v13, v[2:3], off offset:2048
	v_lshl_add_u64 v[2:3], v[2:3], 0, s[2:3]
	global_load_dword v14, v[2:3], off
	global_load_dword v15, v[2:3], off offset:2048
	v_lshl_add_u64 v[2:3], v[2:3], 0, s[2:3]
	global_load_dword v16, v[2:3], off
	global_load_dword v17, v[2:3], off offset:2048
	v_lshl_add_u64 v[2:3], v[2:3], 0, s[2:3]
	global_load_dword v18, v[2:3], off
	global_load_dword v19, v[2:3], off offset:2048
	v_lshl_add_u64 v[2:3], v[2:3], 0, s[2:3]
	global_load_dword v20, v[2:3], off
	global_load_dword v21, v[2:3], off offset:2048
	v_lshl_add_u64 v[2:3], v[2:3], 0, s[2:3]
	global_load_dword v22, v[2:3], off
	global_load_dword v23, v[2:3], off offset:2048
	v_lshl_add_u64 v[2:3], v[2:3], 0, s[2:3]
	global_load_dword v24, v[2:3], off
	global_load_dword v25, v[2:3], off offset:2048
	s_waitcnt vmcnt(0)
	v_mul_f32_e32 v26, 0xbfb8aa3b, v10
	v_mul_f32_e32 v27, 0xbfb8aa3b, v11
	v_mul_f32_e32 v28, 0xbfb8aa3b, v12
	v_mul_f32_e32 v29, 0xbfb8aa3b, v13
	v_mul_f32_e32 v30, 0xbfb8aa3b, v14
	v_mul_f32_e32 v31, 0xbfb8aa3b, v15
	v_mul_f32_e32 v32, 0xbfb8aa3b, v16
	v_mul_f32_e32 v33, 0xbfb8aa3b, v17
	v_mul_f32_e32 v34, 0xbfb8aa3b, v18
	v_mul_f32_e32 v35, 0xbfb8aa3b, v19
	v_mul_f32_e32 v36, 0xbfb8aa3b, v20
	v_mul_f32_e32 v37, 0xbfb8aa3b, v21
	v_mul_f32_e32 v38, 0xbfb8aa3b, v22
	v_mul_f32_e32 v39, 0xbfb8aa3b, v23
	v_mul_f32_e32 v40, 0xbfb8aa3b, v24
	v_mul_f32_e32 v41, 0xbfb8aa3b, v25
	v_exp_f32_e32 v26, v26
	v_exp_f32_e32 v27, v27
	v_exp_f32_e32 v28, v28
	v_exp_f32_e32 v29, v29
	v_exp_f32_e32 v30, v30
	v_exp_f32_e32 v31, v31
	v_exp_f32_e32 v32, v32
	v_exp_f32_e32 v33, v33
	v_exp_f32_e32 v34, v34
	v_exp_f32_e32 v35, v35
	v_exp_f32_e32 v36, v36
	v_exp_f32_e32 v37, v37
	v_exp_f32_e32 v38, v38
	v_exp_f32_e32 v39, v39
	v_exp_f32_e32 v40, v40
	v_exp_f32_e32 v41, v41
	v_add_f32_e32 v26, 1.0, v26
	v_add_f32_e32 v27, 1.0, v27
	v_add_f32_e32 v28, 1.0, v28
	v_add_f32_e32 v29, 1.0, v29
	v_add_f32_e32 v30, 1.0, v30
	v_add_f32_e32 v31, 1.0, v31
	v_add_f32_e32 v32, 1.0, v32
	v_add_f32_e32 v33, 1.0, v33
	v_add_f32_e32 v34, 1.0, v34
	v_add_f32_e32 v35, 1.0, v35
	v_add_f32_e32 v36, 1.0, v36
	v_add_f32_e32 v37, 1.0, v37
	v_add_f32_e32 v38, 1.0, v38
	v_add_f32_e32 v39, 1.0, v39
	v_add_f32_e32 v40, 1.0, v40
	v_add_f32_e32 v41, 1.0, v41
	v_rcp_f32_e32 v26, v26
	v_rcp_f32_e32 v27, v27
	v_rcp_f32_e32 v28, v28
	v_rcp_f32_e32 v29, v29
	v_rcp_f32_e32 v30, v30
	v_rcp_f32_e32 v31, v31
	v_rcp_f32_e32 v32, v32
	v_rcp_f32_e32 v33, v33
	v_rcp_f32_e32 v34, v34
	v_rcp_f32_e32 v35, v35
	v_rcp_f32_e32 v36, v36
	v_rcp_f32_e32 v37, v37
	v_rcp_f32_e32 v38, v38
	v_rcp_f32_e32 v39, v39
	v_rcp_f32_e32 v40, v40
	v_rcp_f32_e32 v41, v41
	v_mul_f32_e32 v10, v10, v26
	v_mul_f32_e32 v11, v11, v27
	v_mul_f32_e32 v12, v12, v28
	v_mul_f32_e32 v13, v13, v29
	v_mul_f32_e32 v14, v14, v30
	v_mul_f32_e32 v15, v15, v31
	v_mul_f32_e32 v16, v16, v32
	v_mul_f32_e32 v17, v17, v33
	v_mul_f32_e32 v18, v18, v34
	v_mul_f32_e32 v19, v19, v35
	v_mul_f32_e32 v20, v20, v36
	v_mul_f32_e32 v21, v21, v37
	v_mul_f32_e32 v22, v22, v38
	v_mul_f32_e32 v23, v23, v39
	v_mul_f32_e32 v24, v24, v40
	v_mul_f32_e32 v25, v25, v41
	ds_write_b32 v4, v10
	ds_write_b32 v4, v11 offset:2048
	ds_write_b32 v4, v12 offset:4096
	ds_write_b32 v4, v13 offset:6144
	ds_write_b32 v4, v14 offset:8192
	ds_write_b32 v4, v15 offset:10240
	ds_write_b32 v4, v16 offset:12288
	ds_write_b32 v4, v17 offset:14336
	ds_write_b32 v4, v18 offset:16384
	ds_write_b32 v4, v19 offset:18432
	ds_write_b32 v4, v20 offset:20480
	ds_write_b32 v4, v21 offset:22528
	ds_write_b32 v4, v22 offset:24576
	ds_write_b32 v4, v23 offset:26624
	ds_write_b32 v4, v24 offset:28672
	ds_write_b32 v4, v25 offset:30720
	s_or_b64 exec, exec, s[0:1]
	s_cmpk_gt_i32 s34, 0xff
	s_waitcnt lgkmcnt(0)
	s_barrier
	s_cbranch_scc1 .LBB0_29
	v_mul_u32_u24_e32 v2, 0xaab, v0
	v_lshrrev_b32_e32 v20, 16, v2
	s_movk_i32 s0, 0x1f8
	v_mul_lo_u16_e32 v2, 24, v20
	v_cmp_gt_u32_e32 vcc, s0, v0
	s_movk_i32 s0, 0xc0
	v_sub_u16_e32 v6, v0, v2
	v_lshrrev_b32_e32 v4, 3, v0
	v_and_b32_e32 v2, 3, v0
	v_cmp_gt_u32_e64 s[2:3], s0, v0
	v_lshl_or_b32 v21, v4, 2, v2
	v_lshlrev_b32_e32 v9, 5, v4
	v_sub_u32_e32 v4, 0xfea, v20
	s_mov_b32 s0, 0xc30c30d
	v_mul_hi_u32 v4, v4, s0
	s_mov_b32 s0, 0xaaaaaab
	v_add_u32_e32 v5, 2, v4
	v_and_b32_e32 v4, 7, v4
	v_mul_hi_u32 v7, v0, s0
	s_mul_hi_i32 s1, s34, 0x180
	s_mul_i32 s0, s34, 0x180
	v_and_b32_e32 v22, 7, v5
	v_cmp_ne_u32_e64 s[4:5], 6, v4
	s_mov_b32 s7, 0x18000
	v_mov_b64_e32 v[4:5], s[0:1]
	v_mad_u64_u32 v[4:5], s[12:13], v7, s7, v[4:5]
	v_readlane_b32 s12, v249, 9
	v_mov_b32_e32 v2, 0
	v_lshlrev_b16_e32 v6, 2, v6
	v_readlane_b32 s16, v249, 13
	v_and_b32_e32 v3, 7, v0
	v_lshlrev_b32_e32 v6, 2, v6
	v_mov_b32_e32 v7, v2
	v_readlane_b32 s17, v249, 14
	s_add_u32 s0, s16, s0
	v_bfe_u32 v1, v0, 2, 1
	v_lshlrev_b32_e32 v8, 5, v0
	v_lshl_add_u32 v3, v3, 2, 0
	v_lshlrev_b32_e32 v23, 2, v20
	v_lshl_add_u64 v[4:5], v[4:5], 0, v[6:7]
	s_addc_u32 s1, s17, s1
	v_mul_u32_u24_e32 v1, 0x6000, v1
	v_add_u32_e32 v24, 0, v23
	v_lshl_add_u64 v[12:13], s[16:17], 0, v[4:5]
	s_mul_hi_i32 s39, s10, 0x180
	s_mul_i32 s38, s10, 0x180
	v_lshl_add_u64 v[14:15], s[0:1], 0, v[6:7]
	s_mov_b64 s[40:41], 0xfc0000
	s_movk_i32 s8, 0xf57
	v_add_u32_e32 v25, 0, v8
	v_add_u32_e32 v26, v3, v9
	s_mov_b32 s11, s34
	v_readlane_b32 s13, v249, 10
	v_readlane_b32 s14, v249, 11
	v_readlane_b32 s15, v249, 12
	v_readlane_b32 s18, v249, 15
	v_readlane_b32 s19, v249, 16
	v_readlane_b32 s20, v249, 17
	v_readlane_b32 s21, v249, 18
	v_readlane_b32 s22, v249, 19
	v_readlane_b32 s23, v249, 20
	v_readlane_b32 s24, v249, 21
	v_readlane_b32 s25, v249, 22
	v_readlane_b32 s26, v249, 23
	v_readlane_b32 s27, v249, 24
	s_branch .LBB0_19
